# P2 phase-order stagger: workgroups with blockIdx bit 3 set run fox_prep before gdn_prep+scan pass 1 so the memory-bound and the VALU-bound sub-phase overlap across the chip
# speedup vs baseline: 1.0013x; 1.0011x over previous
; DI void gdn_load(const Params& P, int u, int tid, u32x4 (&raw)[12], float& sb, float& sa) {
;     const int h = u & 7, n = u >> 3, t = tid >> 3, c8 = tid & 7, tok = n * 64 + t;
;     const bf16_t* PROJ = (const bf16_t*)(P.ws + WS_PROJ); const float* SM = (const float*)(P.ws + WS_SMALL);
; #pragma unroll
;     for (int xx = 0; xx < 3; ++xx)
; #pragma unroll
;         for (int j = 0; j < 4; ++j) { const int tk = tok - 3 + j; u32x4 v = {0u, 0u, 0u, 0u};
;             if (tk >= 0) v = *(const u32x4*)(PROJ + (size_t)xx * BUF_ELEMS + h * 64 + 8 * c8 + (size_t)tk * 512);
; __global__ void __launch_bounds__(512, 2) mega_fwd(Params P) {
;     ...
;     if (G == 256) {
;       const int hb = (int)blockIdx.x & 7, gb = (int)blockIdx.x >> 3;
;       { u32x4 raw[12]; float sbv = 0.f, sav = 0.f;
;         gdn_load(P, (8 * gb) * 8 + hb, tid, raw, sbv, sav);
;         for (int i = tid; i < 768; i += 512) { const int j = i / 192, r = i % 192; ((float*)(lds + 86016))[i] = P.in[4][j * 1536 + (r >> 6) * 512 + hb * 64 + (r & 63)]; }
;         __syncthreads();
;         for (int k = 0; k < 8; ++k) gdn_prep_unit(P, hb, 8 * gb + k, lds, tid, raw, sbv, sav, k < 7 ? (8 * gb + k + 1) * 8 + hb : -1, true); }
.LBB0_456:
	s_and_b64 vcc, exec, s[0:1]
	s_cbranch_vccz .LBB0_659
	s_mov_b32 s99, 0
	s_bitcmp1_b32 s60, 3
	s_cbranch_scc0 .Lp2_gdn
	s_mov_b32 s99, 1
	v_and_b32_e32 v117, 56, v130
	v_and_b32_e32 v122, 7, v162
	v_and_b32_e32 v123, 0x3c0, v162
	s_branch .LBB0_588
.Lp2_gdn:
	s_and_b32 s61, s60, 7
	s_and_b32 s54, s60, -8
	s_lshl_b32 s2, s54, 6
	s_lshl_b32 s0, s61, 7
	v_mov_b32_e32 v2, 0
	s_add_u32 s0, s66, s0
	v_and_b32_e32 v117, 56, v130
	v_mov_b32_e32 v4, v2
	v_mov_b32_e32 v5, v2
	s_waitcnt vmcnt(0)
	v_or_b32_e32 v42, s2, v196
	s_addc_u32 s1, s67, 0
	v_lshlrev_b32_e32 v52, 1, v117
	v_mov_b32_e32 v53, v2
	v_mov_b32_e32 v3, v2
	v_mov_b64_e32 v[8:9], v[4:5]
	v_add_u32_e32 v44, -3, v42
	v_lshl_add_u64 v[34:35], s[0:1], 0, v[52:53]
	v_cmp_lt_i32_e64 s[8:9], 2, v42
	v_mov_b64_e32 v[6:7], v[2:3]
	s_and_saveexec_b64 s[0:1], s[8:9]
	s_cbranch_execz .LBB0_459
	v_mov_b32_e32 v45, v2
	v_lshlrev_b64 v[6:7], 10, v[44:45]
	v_lshl_add_u64 v[6:7], v[34:35], 0, v[6:7]
	global_load_dwordx4 v[6:9], v[6:7], off

; __global__ void __launch_bounds__(512, 2) mega_fwd(Params P) {
;     ...
;       __syncthreads();
;       gdn_scan<true>(P, hb, gb, lds, ldsl, tid);
;       __syncthreads();
;       for (int n = blockIdx.x; n < 256; n += G) fox_prep_unit(P, n, lds, tid);
;       if ((G & 7) == 0) xcd_barrier(bar); else grid.sync();
.LBB0_588:
	s_cmp_eq_u32 s99, 2
	s_cbranch_scc0 .Lp2_fox
	s_ashr_i32 s61, s60, 31
	s_waitcnt vmcnt(0) lgkmcnt(0)
	s_barrier
	s_branch .LBB0_593

; __global__ void __launch_bounds__(512, 2) mega_fwd(Params P) {
;     ...
;     if (G == 256) {
;       const int hb = (int)blockIdx.x & 7, gb = (int)blockIdx.x >> 3;
;       { u32x4 raw[12]; float sbv = 0.f, sav = 0.f;
;     ...
;       for (int n = blockIdx.x; n < 256; n += G) fox_prep_unit(P, n, lds, tid);
;       if ((G & 7) == 0) xcd_barrier(bar); else grid.sync();
.LBB0_593:
	s_cmp_eq_u32 s99, 1
	s_cbranch_scc0 .Lp2_after
	s_mov_b32 s99, 2
	v_lshlrev_b32_e32 v130, 3, v162
	v_lshlrev_b32_e32 v131, 1, v1
	s_waitcnt vmcnt(0) lgkmcnt(0)
	s_barrier
	s_branch .Lp2_gdn
